# stack2 + EpiMerge FIRST: second-half gate loads hoisted beside first-half loads (no store-drain wait)
# speedup vs baseline: 1.0026x; 1.0020x over previous
; __device__ __forceinline__ u32x4 pack8(const f32x4 v0, const f32x4 v1) { u32x4 w; w.x = cvt_pk_bf16(v0[0], v0[1]); w.y = cvt_pk_bf16(v0[2], v0[3]); w.z = cvt_pk_bf16(v1[0], v1[1]); w.w = cvt_pk_bf16(v1[2], v1[3]); return w; }
;     __device__ __forceinline__ void operator()(const f32x4 (&acc)[2][2][4][2], const Unit& u, int wr, int wc, int fr_, int fq) const {
;     ...
;         const size_t row0 = (size_t)u.pm * BM + wr * 64 + fr; const int col0 = u.pn * BM + wc * 32 + 8 * fq;
; #pragma unroll
;         for (int ai = 0; ai < 2; ++ai) {
;             u32x4 gw[4][2], ow[4][2];
; #pragma unroll
;             for (int m = 0; m < 4; ++m)
; #pragma unroll
;                 for (int bj = 0; bj < 2; ++bj) { const size_t r = row0 + ai * HALF + m * 16; const int c = col0 + bj * HALF;
;                     gw[m][bj] = *(const u32x4*)(G + r * 6144 + goff + c); if (!FIRST) ow[m][bj] = *(const u32x4*)(Mo + r * DM + c); }
; #pragma unroll
;             for (int m = 0; m < 4; ++m)
; #pragma unroll
;                 for (int bj = 0; bj < 2; ++bj) { const size_t r = row0 + ai * HALF + m * 16; const int c = col0 + bj * HALF;
;                     f32x4 g0, g1; unpack8(gw[m][bj], g0, g1);
;                     f32x4 v0 = g0 * acc[ai][bj][m][0], v1 = g1 * acc[ai][bj][m][1];
;                     if (!FIRST) { f32x4 o0, o1; unpack8(ow[m][bj], o0, o1); v0 += o0; v1 += o1; }
;                     *(u32x4*)((Mdst ? Mdst : Mo) + r * DM + c) = pack8(v0, v1); }
.LBB0_1120:
	s_ashr_i32 s31, s30, 31
	s_lshl_b64 s[0:1], s[30:31], 8
	v_mov_b32_e32 v130, v162
	s_add_u32 s0, s0, s73
	s_addc_u32 s1, s1, s89
	v_ashrrev_i32_e32 v131, 31, v130
	v_lshl_add_u64 v[178:179], s[0:1], 0, v[130:131]
	v_lshl_or_b32 v130, s28, 8, v164
	v_mov_b64_e32 v[132:133], s[14:15]
	s_movk_i32 s21, 0x3000
	v_ashrrev_i32_e32 v131, 31, v130
	v_mad_u64_u32 v[132:133], s[0:1], v178, s21, v[132:133]
	v_mad_i32_i24 v133, v179, s21, v133
	v_lshlrev_b64 v[180:181], 1, v[130:131]
	v_lshl_add_u64 v[160:161], v[132:133], 0, v[180:181]
	global_load_dwordx4 v[166:169], v[160:161], off
	global_load_dwordx4 v[170:173], v[160:161], off offset:256
	s_mov_b32 s91, 0x30000
	v_add_co_u32_e32 v132, vcc, s91, v160
	s_mov_b64 s[34:35], 0x30000
	s_nop 0
	v_addc_co_u32_e32 v133, vcc, 0, v161, vcc
	v_lshl_add_u64 v[130:131], v[160:161], 0, s[34:35]
	global_load_dwordx4 v[174:177], v[132:133], off
	global_load_dwordx4 v[146:149], v[130:131], off offset:256
	s_mov_b32 s94, 0x60000
	v_add_co_u32_e32 v132, vcc, s94, v160
	s_mov_b64 s[0:1], 0x60000
	s_nop 0
	v_addc_co_u32_e32 v133, vcc, 0, v161, vcc
	v_lshl_add_u64 v[130:131], v[160:161], 0, s[0:1]
	global_load_dwordx4 v[142:145], v[132:133], off
	global_load_dwordx4 v[138:141], v[130:131], off offset:256
	s_mov_b32 s0, 0x90000
	s_mov_b64 s[36:37], 0x90000
	v_add_co_u32_e32 v132, vcc, s0, v160
	v_lshl_add_u64 v[130:131], v[160:161], 0, s[36:37]
	s_nop 0
	v_addc_co_u32_e32 v133, vcc, 0, v161, vcc
	global_load_dwordx4 v[134:137], v[132:133], off
	s_nop 0
	global_load_dwordx4 v[130:133], v[130:131], off offset:256
	v_add_co_u32_e32 v188, vcc, 0x180000, v160
	s_nop 1
	v_addc_co_u32_e32 v189, vcc, 0, v161, vcc
	s_nop 0
	global_load_dwordx4 v[204:207], v[188:189], off
	global_load_dwordx4 v[208:211], v[188:189], off offset:256
	v_add_co_u32_e32 v188, vcc, 0x1b0000, v160
	s_nop 1
	v_addc_co_u32_e32 v189, vcc, 0, v161, vcc
	s_nop 0
	global_load_dwordx4 v[212:215], v[188:189], off
	global_load_dwordx4 v[216:219], v[188:189], off offset:256
	v_add_co_u32_e32 v188, vcc, 0x1e0000, v160
	s_nop 1
	v_addc_co_u32_e32 v189, vcc, 0, v161, vcc
	s_nop 0
	global_load_dwordx4 v[220:223], v[188:189], off
	global_load_dwordx4 v[224:227], v[188:189], off offset:256
	v_add_co_u32_e32 v188, vcc, 0x210000, v160
	s_nop 1
	v_addc_co_u32_e32 v189, vcc, 0, v161, vcc
	s_nop 0
	global_load_dwordx4 v[200:203], v[188:189], off
	global_load_dwordx4 v[196:199], v[188:189], off offset:256
	v_lshlrev_b64 v[178:179], 12, v[178:179]
	s_mov_b64 s[30:31], 0x20000
	s_mov_b32 s1, 0x180000
	s_mov_b32 s52, 0x80000
	s_waitcnt vmcnt(8)
	v_lshlrev_b32_e32 v182, 16, v166
	v_and_b32_e32 v183, 0xffff0000, v166
	v_lshlrev_b32_e32 v184, 16, v168
	v_and_b32_e32 v185, 0xffff0000, v168
	v_lshlrev_b32_e32 v166, 16, v167
	v_and_b32_e32 v167, 0xffff0000, v167
	v_lshlrev_b32_e32 v168, 16, v169
	v_and_b32_e32 v169, 0xffff0000, v169
	v_pk_mul_f32 v[126:127], v[126:127], v[182:183]
	v_pk_mul_f32 v[122:123], v[122:123], v[184:185]
	v_pk_mul_f32 v[128:129], v[128:129], v[166:167]
	v_pk_mul_f32 v[166:167], v[124:125], v[168:169]
	v_cvt_pk_bf16_f32 v124, v126, v127
	v_cvt_pk_bf16_f32 v125, v128, v129
	v_cvt_pk_bf16_f32 v126, v122, v123
	v_lshl_add_u64 v[122:123], s[2:3], 0, v[178:179]
	v_lshl_add_u64 v[122:123], v[122:123], 0, v[180:181]
	v_cvt_pk_bf16_f32 v127, v166, v167
	global_store_dwordx4 v[122:123], v[124:127], off
	v_lshlrev_b32_e32 v128, 16, v172
	v_and_b32_e32 v129, 0xffff0000, v172
	v_lshlrev_b32_e32 v124, 16, v170
	v_and_b32_e32 v125, 0xffff0000, v170
	v_lshlrev_b32_e32 v166, 16, v173
	v_and_b32_e32 v167, 0xffff0000, v173
	v_lshlrev_b32_e32 v126, 16, v171
	v_and_b32_e32 v127, 0xffff0000, v171
	v_pk_mul_f32 v[110:111], v[110:111], v[124:125]
	v_pk_mul_f32 v[124:125], v[108:109], v[166:167]
	v_pk_mul_f32 v[108:109], v[106:107], v[128:129]
	v_pk_mul_f32 v[112:113], v[112:113], v[126:127]
	v_cvt_pk_bf16_f32 v106, v110, v111
	v_lshlrev_b32_e32 v110, 16, v176
	v_cvt_pk_bf16_f32 v107, v112, v113
	v_cvt_pk_bf16_f32 v108, v108, v109
	v_cvt_pk_bf16_f32 v109, v124, v125
	global_store_dwordx4 v[122:123], v[106:109], off offset:256
	v_lshlrev_b32_e32 v112, 16, v177
	v_and_b32_e32 v113, 0xffff0000, v177
	v_lshlrev_b32_e32 v106, 16, v174
	v_and_b32_e32 v107, 0xffff0000, v174
	v_lshlrev_b32_e32 v108, 16, v175
	v_and_b32_e32 v109, 0xffff0000, v175
	v_and_b32_e32 v111, 0xffff0000, v176
	v_pk_mul_f32 v[108:109], v[120:121], v[108:109]
	v_pk_mul_f32 v[106:107], v[118:119], v[106:107]
	v_pk_mul_f32 v[112:113], v[116:117], v[112:113]
	v_pk_mul_f32 v[110:111], v[114:115], v[110:111]
	v_cvt_pk_bf16_f32 v106, v106, v107
	v_cvt_pk_bf16_f32 v107, v108, v109
	v_lshlrev_b32_e32 v114, 16, v149
	v_cvt_pk_bf16_f32 v108, v110, v111
	v_cvt_pk_bf16_f32 v109, v112, v113
	v_add_co_u32_e32 v112, vcc, s80, v122
	v_and_b32_e32 v115, 0xffff0000, v149
	s_nop 0
	v_addc_co_u32_e32 v113, vcc, 0, v123, vcc
	global_store_dwordx4 v[112:113], v[106:109], off
	v_lshlrev_b32_e32 v112, 16, v148
	v_and_b32_e32 v113, 0xffff0000, v148
	v_lshlrev_b32_e32 v106, 16, v146
	v_and_b32_e32 v107, 0xffff0000, v146
	v_lshlrev_b32_e32 v108, 16, v147
	v_and_b32_e32 v109, 0xffff0000, v147
	v_pk_mul_f32 v[102:103], v[102:103], v[106:107]
	v_pk_mul_f32 v[106:107], v[100:101], v[114:115]
	v_pk_mul_f32 v[100:101], v[98:99], v[112:113]
	v_lshl_add_u64 v[110:111], v[122:123], 0, s[48:49]
	v_pk_mul_f32 v[104:105], v[104:105], v[108:109]
	v_cvt_pk_bf16_f32 v98, v102, v103
	v_lshlrev_b32_e32 v102, 16, v144
	v_cvt_pk_bf16_f32 v99, v104, v105
	v_cvt_pk_bf16_f32 v100, v100, v101
	v_cvt_pk_bf16_f32 v101, v106, v107
	global_store_dwordx4 v[110:111], v[98:101], off offset:256
	v_and_b32_e32 v103, 0xffff0000, v144
	v_lshlrev_b32_e32 v104, 16, v145
; __device__ __forceinline__ u32x4 pack8(const f32x4 v0, const f32x4 v1) { u32x4 w; w.x = cvt_pk_bf16(v0[0], v0[1]); w.y = cvt_pk_bf16(v0[2], v0[3]); w.z = cvt_pk_bf16(v1[0], v1[1]); w.w = cvt_pk_bf16(v1[2], v1[3]); return w; }
;     __device__ __forceinline__ void operator()(const f32x4 (&acc)[2][2][4][2], const Unit& u, int wr, int wc, int fr_, int fq) const {
;     ...
;                 for (int bj = 0; bj < 2; ++bj) { const size_t r = row0 + ai * HALF + m * 16; const int c = col0 + bj * HALF;
;                     gw[m][bj] = *(const u32x4*)(G + r * 6144 + goff + c); if (!FIRST) ow[m][bj] = *(const u32x4*)(Mo + r * DM + c); }
; #pragma unroll
;             for (int m = 0; m < 4; ++m)
; #pragma unroll
;                 for (int bj = 0; bj < 2; ++bj) { const size_t r = row0 + ai * HALF + m * 16; const int c = col0 + bj * HALF;
;                     f32x4 g0, g1; unpack8(gw[m][bj], g0, g1);
;                     f32x4 v0 = g0 * acc[ai][bj][m][0], v1 = g1 * acc[ai][bj][m][1];
;                     if (!FIRST) { f32x4 o0, o1; unpack8(ow[m][bj], o0, o1); v0 += o0; v1 += o1; }
;                     *(u32x4*)((Mdst ? Mdst : Mo) + r * DM + c) = pack8(v0, v1); }
;             asm volatile("" ::: "memory"); }
	v_lshlrev_b32_e32 v100, 16, v143
	v_and_b32_e32 v101, 0xffff0000, v143
	v_lshlrev_b32_e32 v98, 16, v142
	v_and_b32_e32 v99, 0xffff0000, v142
	v_and_b32_e32 v105, 0xffff0000, v145
	v_pk_mul_f32 v[96:97], v[96:97], v[100:101]
	v_pk_mul_f32 v[94:95], v[94:95], v[98:99]
	v_pk_mul_f32 v[98:99], v[92:93], v[104:105]
	v_pk_mul_f32 v[92:93], v[90:91], v[102:103]
	v_cvt_pk_bf16_f32 v90, v94, v95
	v_cvt_pk_bf16_f32 v91, v96, v97
	v_add_co_u32_e32 v96, vcc, s95, v122
	v_cvt_pk_bf16_f32 v92, v92, v93
	v_cvt_pk_bf16_f32 v93, v98, v99
	v_lshlrev_b32_e32 v98, 16, v141
	s_nop 0
	v_addc_co_u32_e32 v97, vcc, 0, v123, vcc
	global_store_dwordx4 v[96:97], v[90:93], off
	v_lshlrev_b32_e32 v96, 16, v140
	v_and_b32_e32 v97, 0xffff0000, v140
	v_lshlrev_b32_e32 v90, 16, v138
	v_and_b32_e32 v91, 0xffff0000, v138
	v_and_b32_e32 v99, 0xffff0000, v141
	v_lshlrev_b32_e32 v92, 16, v139
	v_and_b32_e32 v93, 0xffff0000, v139
	v_pk_mul_f32 v[86:87], v[86:87], v[90:91]
	v_pk_mul_f32 v[90:91], v[84:85], v[98:99]
	v_pk_mul_f32 v[84:85], v[82:83], v[96:97]
	v_lshl_add_u64 v[94:95], v[122:123], 0, s[30:31]
	v_pk_mul_f32 v[88:89], v[88:89], v[92:93]
	v_cvt_pk_bf16_f32 v82, v86, v87
	v_lshlrev_b32_e32 v86, 16, v136
	v_cvt_pk_bf16_f32 v83, v88, v89
	v_cvt_pk_bf16_f32 v84, v84, v85
	v_cvt_pk_bf16_f32 v85, v90, v91
	global_store_dwordx4 v[94:95], v[82:85], off offset:256
	v_and_b32_e32 v87, 0xffff0000, v136
	v_lshlrev_b32_e32 v88, 16, v137
	v_lshlrev_b32_e32 v84, 16, v135
	v_and_b32_e32 v85, 0xffff0000, v135
	v_lshlrev_b32_e32 v82, 16, v134
	v_and_b32_e32 v83, 0xffff0000, v134
	v_and_b32_e32 v89, 0xffff0000, v137
	v_pk_mul_f32 v[80:81], v[80:81], v[84:85]
	v_pk_mul_f32 v[78:79], v[78:79], v[82:83]
	v_pk_mul_f32 v[82:83], v[76:77], v[88:89]
	v_pk_mul_f32 v[76:77], v[74:75], v[86:87]
	v_cvt_pk_bf16_f32 v74, v78, v79
	v_cvt_pk_bf16_f32 v75, v80, v81
	v_add_co_u32_e32 v80, vcc, s91, v122
	v_cvt_pk_bf16_f32 v76, v76, v77
	v_cvt_pk_bf16_f32 v77, v82, v83
	v_lshlrev_b32_e32 v82, 16, v133
	s_nop 0
	v_addc_co_u32_e32 v81, vcc, 0, v123, vcc
	global_store_dwordx4 v[80:81], v[74:77], off
	v_lshlrev_b32_e32 v80, 16, v132
	v_and_b32_e32 v81, 0xffff0000, v132
	v_lshlrev_b32_e32 v74, 16, v130
	v_and_b32_e32 v75, 0xffff0000, v130
	v_and_b32_e32 v83, 0xffff0000, v133
	v_lshlrev_b32_e32 v76, 16, v131
	v_and_b32_e32 v77, 0xffff0000, v131
	v_pk_mul_f32 v[70:71], v[70:71], v[74:75]
	v_pk_mul_f32 v[74:75], v[68:69], v[82:83]
	v_pk_mul_f32 v[68:69], v[66:67], v[80:81]
	v_lshl_add_u64 v[78:79], v[122:123], 0, s[34:35]
	v_pk_mul_f32 v[72:73], v[72:73], v[76:77]
	v_cvt_pk_bf16_f32 v66, v70, v71
	s_mov_b64 s[30:31], 0x180000
	v_cvt_pk_bf16_f32 v67, v72, v73
	v_cvt_pk_bf16_f32 v68, v68, v69
	v_cvt_pk_bf16_f32 v69, v74, v75
	global_store_dwordx4 v[78:79], v[66:69], off offset:256
	s_nop 1
	s_mov_b64 s[30:31], 0x80000
	s_waitcnt vmcnt(15)
	v_lshlrev_b32_e32 v98, 16, v204
	v_and_b32_e32 v99, 0xffff0000, v204
	v_lshlrev_b32_e32 v204, 16, v205
	v_and_b32_e32 v205, 0xffff0000, v205
	v_lshlrev_b32_e32 v100, 16, v206
	v_and_b32_e32 v101, 0xffff0000, v206
	v_lshlrev_b32_e32 v206, 16, v207
	v_and_b32_e32 v207, 0xffff0000, v207
	v_pk_mul_f32 v[64:65], v[64:65], v[204:205]
	v_pk_mul_f32 v[62:63], v[62:63], v[98:99]
	v_pk_mul_f32 v[204:205], v[60:61], v[206:207]
	v_pk_mul_f32 v[60:61], v[58:59], v[100:101]
	v_cvt_pk_bf16_f32 v58, v62, v63
	v_cvt_pk_bf16_f32 v59, v64, v65
	v_add_co_u32_e32 v64, vcc, s52, v122
	v_cvt_pk_bf16_f32 v60, v60, v61
	v_cvt_pk_bf16_f32 v61, v204, v205
	s_waitcnt vmcnt(14)
	v_lshlrev_b32_e32 v204, 16, v211
	v_addc_co_u32_e32 v65, vcc, 0, v123, vcc
	global_store_dwordx4 v[64:65], v[58:61], off
	v_lshlrev_b32_e32 v64, 16, v210
	v_and_b32_e32 v65, 0xffff0000, v210
	v_lshlrev_b32_e32 v58, 16, v208
	v_and_b32_e32 v59, 0xffff0000, v208
	v_and_b32_e32 v205, 0xffff0000, v211
	v_lshlrev_b32_e32 v60, 16, v209
	v_and_b32_e32 v61, 0xffff0000, v209
	v_pk_mul_f32 v[54:55], v[54:55], v[58:59]
	v_pk_mul_f32 v[58:59], v[52:53], v[204:205]
	v_pk_mul_f32 v[52:53], v[50:51], v[64:65]
	v_lshl_add_u64 v[62:63], v[122:123], 0, s[30:31]
	v_pk_mul_f32 v[56:57], v[56:57], v[60:61]
	v_cvt_pk_bf16_f32 v50, v54, v55
	s_waitcnt vmcnt(14)
; __device__ __forceinline__ u32x4 pack8(const f32x4 v0, const f32x4 v1) { u32x4 w; w.x = cvt_pk_bf16(v0[0], v0[1]); w.y = cvt_pk_bf16(v0[2], v0[3]); w.z = cvt_pk_bf16(v1[0], v1[1]); w.w = cvt_pk_bf16(v1[2], v1[3]); return w; }
;     __device__ __forceinline__ void operator()(const f32x4 (&acc)[2][2][4][2], const Unit& u, int wr, int wc, int fr_, int fq) const {
;     ...
;                 for (int bj = 0; bj < 2; ++bj) { const size_t r = row0 + ai * HALF + m * 16; const int c = col0 + bj * HALF;
;                     gw[m][bj] = *(const u32x4*)(G + r * 6144 + goff + c); if (!FIRST) ow[m][bj] = *(const u32x4*)(Mo + r * DM + c); }
; #pragma unroll
;             for (int m = 0; m < 4; ++m)
; #pragma unroll
;                 for (int bj = 0; bj < 2; ++bj) { const size_t r = row0 + ai * HALF + m * 16; const int c = col0 + bj * HALF;
;                     f32x4 g0, g1; unpack8(gw[m][bj], g0, g1);
;                     f32x4 v0 = g0 * acc[ai][bj][m][0], v1 = g1 * acc[ai][bj][m][1];
;                     if (!FIRST) { f32x4 o0, o1; unpack8(ow[m][bj], o0, o1); v0 += o0; v1 += o1; }
;                     *(u32x4*)((Mdst ? Mdst : Mo) + r * DM + c) = pack8(v0, v1); }
;             asm volatile("" ::: "memory"); }
	v_lshlrev_b32_e32 v54, 16, v214
	v_cvt_pk_bf16_f32 v51, v56, v57
	v_cvt_pk_bf16_f32 v52, v52, v53
	v_cvt_pk_bf16_f32 v53, v58, v59
	global_store_dwordx4 v[62:63], v[50:53], off offset:256
	v_and_b32_e32 v55, 0xffff0000, v214
	v_lshlrev_b32_e32 v56, 16, v215
	v_lshlrev_b32_e32 v52, 16, v213
	v_and_b32_e32 v53, 0xffff0000, v213
	v_lshlrev_b32_e32 v50, 16, v212
	v_and_b32_e32 v51, 0xffff0000, v212
	v_and_b32_e32 v57, 0xffff0000, v215
	v_pk_mul_f32 v[48:49], v[48:49], v[52:53]
	v_pk_mul_f32 v[46:47], v[46:47], v[50:51]
	v_pk_mul_f32 v[50:51], v[44:45], v[56:57]
	v_pk_mul_f32 v[44:45], v[42:43], v[54:55]
	v_cvt_pk_bf16_f32 v42, v46, v47
	v_cvt_pk_bf16_f32 v43, v48, v49
	v_add_co_u32_e32 v48, vcc, s0, v122
	v_cvt_pk_bf16_f32 v44, v44, v45
	v_cvt_pk_bf16_f32 v45, v50, v51
	s_waitcnt vmcnt(14)
	v_lshlrev_b32_e32 v50, 16, v219
	v_addc_co_u32_e32 v49, vcc, 0, v123, vcc
	global_store_dwordx4 v[48:49], v[42:45], off
	v_lshlrev_b32_e32 v48, 16, v218
	v_and_b32_e32 v49, 0xffff0000, v218
	v_lshlrev_b32_e32 v42, 16, v216
	v_and_b32_e32 v43, 0xffff0000, v216
	v_lshlrev_b32_e32 v44, 16, v217
	v_and_b32_e32 v45, 0xffff0000, v217
	v_and_b32_e32 v51, 0xffff0000, v219
	v_lshl_add_u64 v[46:47], v[122:123], 0, s[36:37]
	v_pk_mul_f32 v[40:41], v[40:41], v[44:45]
	v_pk_mul_f32 v[38:39], v[38:39], v[42:43]
	v_pk_mul_f32 v[42:43], v[36:37], v[50:51]
	v_pk_mul_f32 v[36:37], v[34:35], v[48:49]
	v_cvt_pk_bf16_f32 v34, v38, v39
	v_cvt_pk_bf16_f32 v35, v40, v41
	s_waitcnt vmcnt(14)
	v_lshlrev_b32_e32 v38, 16, v222
	v_cvt_pk_bf16_f32 v36, v36, v37
	v_cvt_pk_bf16_f32 v37, v42, v43
	global_store_dwordx4 v[46:47], v[34:37], off offset:256
	v_and_b32_e32 v39, 0xffff0000, v222
	v_lshlrev_b32_e32 v40, 16, v223
	v_lshlrev_b32_e32 v34, 16, v220
	v_and_b32_e32 v35, 0xffff0000, v220
	v_lshlrev_b32_e32 v36, 16, v221
	v_and_b32_e32 v37, 0xffff0000, v221
	v_and_b32_e32 v41, 0xffff0000, v223
	v_pk_mul_f32 v[30:31], v[30:31], v[34:35]
	s_mov_b64 s[0:1], 0xa0000
	v_pk_mul_f32 v[32:33], v[32:33], v[36:37]
	v_pk_mul_f32 v[34:35], v[28:29], v[40:41]
	v_pk_mul_f32 v[28:29], v[26:27], v[38:39]
	v_cvt_pk_bf16_f32 v26, v30, v31
	v_lshl_add_u64 v[30:31], v[122:123], 0, s[0:1]
	s_mov_b32 s0, 0xa0000
	v_cvt_pk_bf16_f32 v27, v32, v33
	v_add_co_u32_e32 v32, vcc, s0, v122
	v_cvt_pk_bf16_f32 v28, v28, v29
	v_cvt_pk_bf16_f32 v29, v34, v35
	s_waitcnt vmcnt(14)
	v_lshlrev_b32_e32 v34, 16, v227
	v_addc_co_u32_e32 v33, vcc, 0, v123, vcc
	global_store_dwordx4 v[32:33], v[26:29], off
	v_lshlrev_b32_e32 v32, 16, v226
	v_and_b32_e32 v33, 0xffff0000, v226
	v_lshlrev_b32_e32 v26, 16, v224
	v_and_b32_e32 v27, 0xffff0000, v224
	v_lshlrev_b32_e32 v28, 16, v225
	v_and_b32_e32 v29, 0xffff0000, v225
	v_and_b32_e32 v35, 0xffff0000, v227
	v_pk_mul_f32 v[24:25], v[24:25], v[28:29]
	v_pk_mul_f32 v[22:23], v[22:23], v[26:27]
	v_pk_mul_f32 v[26:27], v[20:21], v[34:35]
	v_pk_mul_f32 v[20:21], v[18:19], v[32:33]
	v_cvt_pk_bf16_f32 v18, v22, v23
	v_cvt_pk_bf16_f32 v19, v24, v25
	s_waitcnt vmcnt(14)
	v_lshlrev_b32_e32 v22, 16, v202
	v_cvt_pk_bf16_f32 v20, v20, v21
	v_cvt_pk_bf16_f32 v21, v26, v27
	global_store_dwordx4 v[30:31], v[18:21], off offset:256
	v_and_b32_e32 v23, 0xffff0000, v202
	v_lshlrev_b32_e32 v24, 16, v203
	v_lshlrev_b32_e32 v18, 16, v200
	v_and_b32_e32 v19, 0xffff0000, v200
	v_lshlrev_b32_e32 v20, 16, v201
	v_and_b32_e32 v21, 0xffff0000, v201
	v_and_b32_e32 v25, 0xffff0000, v203
	v_pk_mul_f32 v[14:15], v[14:15], v[18:19]
	s_mov_b64 s[0:1], 0xb0000
	v_pk_mul_f32 v[16:17], v[16:17], v[20:21]
	v_pk_mul_f32 v[18:19], v[12:13], v[24:25]
	v_pk_mul_f32 v[12:13], v[10:11], v[22:23]
	v_cvt_pk_bf16_f32 v10, v14, v15
	v_lshl_add_u64 v[14:15], v[122:123], 0, s[0:1]
	s_mov_b32 s0, 0xb0000
	v_cvt_pk_bf16_f32 v11, v16, v17
	v_add_co_u32_e32 v16, vcc, s0, v122
	v_cvt_pk_bf16_f32 v12, v12, v13
	v_cvt_pk_bf16_f32 v13, v18, v19
	s_waitcnt vmcnt(14)
	v_lshlrev_b32_e32 v18, 16, v199
	v_addc_co_u32_e32 v17, vcc, 0, v123, vcc
	global_store_dwordx4 v[16:17], v[10:13], off
	v_lshlrev_b32_e32 v16, 16, v198
	v_and_b32_e32 v17, 0xffff0000, v198
	v_lshlrev_b32_e32 v10, 16, v196
	v_and_b32_e32 v11, 0xffff0000, v196
	v_and_b32_e32 v19, 0xffff0000, v199
	v_lshlrev_b32_e32 v12, 16, v197
	v_and_b32_e32 v13, 0xffff0000, v197
	v_pk_mul_f32 v[6:7], v[6:7], v[10:11]
	v_pk_mul_f32 v[10:11], v[4:5], v[18:19]
	v_pk_mul_f32 v[4:5], v[2:3], v[16:17]
	v_pk_mul_f32 v[8:9], v[8:9], v[12:13]
	v_cvt_pk_bf16_f32 v2, v6, v7
	s_mov_b64 s[0:1], -1
	v_cvt_pk_bf16_f32 v3, v8, v9
	v_cvt_pk_bf16_f32 v4, v4, v5
	v_cvt_pk_bf16_f32 v5, v10, v11
	global_store_dwordx4 v[14:15], v[2:5], off offset:256
	s_andn2_b64 vcc, exec, s[6:7]
	s_cbranch_vccnz .LBB0_1110
	s_andn2_b64 vcc, exec, s[12:13]
	s_cbranch_vccnz .LBB0_1109
	s_barrier
	s_branch .LBB0_1109
